# final norm: dropped the early full wait on the norm-weight loads (first consumer is after the row loads)
# speedup vs baseline: 1.0064x; 1.0017x over previous
.LBB0_80:
.LBB0_81:
	s_load_dwordx2 s[4:5], s[0:1], 0xc8
	s_mov_b64 s[8:9], -1
	s_mov_b64 s[6:7], 0
	s_waitcnt lgkmcnt(0)
	s_add_u32 s4, s4, 0x100000
	s_addc_u32 s5, s5, 0
	v_writelane_b32 v255, s4, 48
	s_cmp_lt_i32 s38, 17
	s_nop 0
	v_writelane_b32 v255, s5, 49
	s_mov_b64 s[4:5], 0
	s_cbranch_scc1 .LBB0_96
	s_cmp_eq_u32 s38, 17
	s_mov_b64 s[6:7], -1
	s_cbranch_scc0 .LBB0_95
	v_mov_b32_e32 v0, v191
	s_nop 0
	v_readfirstlane_b32 s3, v0
	s_ashr_i32 s3, s3, 6
	s_add_i32 s6, s3, s40
	s_cmpk_gt_i32 s6, 0x3fff
	s_cbranch_scc1 .LBB0_94
	s_load_dwordx2 s[8:9], s[0:1], 0xb8
	v_lshlrev_b32_e32 v0, 4, v0
	v_readlane_b32 s10, v255, 14
	v_readlane_b32 s11, v255, 15
	v_and_b32_e32 v0, 0x3f0, v0
	s_load_dwordx2 s[10:11], s[10:11], 0x0
	s_waitcnt lgkmcnt(0)
	global_load_dwordx4 v[2:5], v0, s[8:9]
	global_load_dwordx4 v[6:9], v0, s[8:9] offset:1024
	global_load_dwordx4 v[10:13], v0, s[8:9] offset:2048
	global_load_dwordx4 v[14:17], v0, s[8:9] offset:3072
	s_nop 0
	v_and_b32_e32 v18, 64, v228
	v_add_u32_e32 v18, 64, v18
	v_xor_b32_e32 v19, 1, v228
	v_cmp_lt_i32_e32 vcc, v19, v18
	v_lshl_add_u64 v[46:47], s[10:11], 0, v[0:1]
	s_nop 0
	v_cndmask_b32_e32 v19, v228, v19, vcc
	v_lshlrev_b32_e32 v58, 2, v19
	v_xor_b32_e32 v19, 2, v228
	v_cmp_lt_i32_e32 vcc, v19, v18
	s_nop 1
	v_cndmask_b32_e32 v19, v228, v19, vcc
	v_lshlrev_b32_e32 v59, 2, v19
	v_xor_b32_e32 v19, 4, v228
	v_cmp_lt_i32_e32 vcc, v19, v18
	s_nop 1
	v_cndmask_b32_e32 v19, v228, v19, vcc
	v_lshlrev_b32_e32 v60, 2, v19
	v_xor_b32_e32 v19, 8, v228
	v_cmp_lt_i32_e32 vcc, v19, v18
	s_nop 1
	v_cndmask_b32_e32 v19, v228, v19, vcc
	v_lshlrev_b32_e32 v61, 2, v19
	v_xor_b32_e32 v19, 16, v228
	v_cmp_lt_i32_e32 vcc, v19, v18
	s_nop 1
	v_cndmask_b32_e32 v19, v228, v19, vcc
	v_lshlrev_b32_e32 v62, 2, v19
	v_xor_b32_e32 v19, 32, v228
	v_cmp_lt_i32_e32 vcc, v19, v18
	s_nop 1
	v_cndmask_b32_e32 v18, v228, v19, vcc
	v_lshlrev_b32_e32 v63, 2, v18
	s_branch .LBB0_86
